# lever 7: LayerNorm row reductions with v_permlane32/16_swap + DPP adds instead of 18 ds_bpermute round trips per iteration
# baseline (speedup 1.0000x reference)
.LBB0_85:
	v_add_u32_e32 v42, s42, v48
	s_mov_b32 s0, 0x8000
	v_ashrrev_i32_e32 v49, 31, v48
	v_cmp_gt_i32_e64 s[38:39], s0, v42
	v_lshlrev_b64 v[2:3], 12, v[48:49]
	v_lshl_add_u64 v[44:45], v[34:35], 0, v[2:3]
	v_cndmask_b32_e64 v2, v48, v42, s[38:39]
	v_ashrrev_i32_e32 v3, 31, v2
	v_lshlrev_b64 v[2:3], 12, v[2:3]
	v_lshl_add_u64 v[2:3], v[34:35], 0, v[2:3]
	global_load_dwordx4 v[30:33], v[44:45], off
	global_load_dwordx4 v[26:29], v[44:45], off offset:1024
	global_load_dwordx4 v[22:25], v[44:45], off offset:2048
	global_load_dwordx4 v[18:21], v[44:45], off offset:3072
	global_load_dwordx4 v[14:17], v[2:3], off
	global_load_dwordx4 v[10:13], v[2:3], off offset:1024
	global_load_dwordx4 v[6:9], v[2:3], off offset:2048
	s_nop 0
	global_load_dwordx4 v[2:5], v[2:3], off offset:3072
	s_mov_b32 s0, 0x3c800000
	s_mov_b32 s1, 0x3a800000
	s_mov_b32 s0, s1
	s_waitcnt vmcnt(6)
	v_pk_add_f32 v[50:51], v[30:31], v[26:27]
	v_pk_add_f32 v[46:47], v[32:33], v[28:29]
	s_waitcnt vmcnt(5)
	v_pk_add_f32 v[50:51], v[50:51], v[22:23]
	v_pk_add_f32 v[46:47], v[46:47], v[24:25]
	s_waitcnt vmcnt(4)
	v_pk_add_f32 v[50:51], v[50:51], v[18:19]
	v_pk_add_f32 v[46:47], v[46:47], v[20:21]
	v_add_f32_e32 v43, v50, v51
	v_add_f32_e32 v43, v46, v43
	s_waitcnt vmcnt(2)
	v_pk_add_f32 v[54:55], v[14:15], v[10:11]
	v_add_f32_e32 v43, v47, v43
	v_pk_add_f32 v[52:53], v[16:17], v[12:13]
	s_waitcnt vmcnt(1)
	v_pk_add_f32 v[54:55], v[54:55], v[6:7]
	v_pk_add_f32 v[52:53], v[52:53], v[8:9]
	s_waitcnt vmcnt(0)
	v_pk_add_f32 v[54:55], v[54:55], v[2:3]
	v_pk_add_f32 v[52:53], v[52:53], v[4:5]
	v_add_f32_e32 v46, v54, v55
	v_add_f32_e32 v46, v52, v46
	v_add_f32_e32 v46, v53, v46
	v_mov_b32_e32 v47, v43
	v_mov_b32_e32 v132, v46
	s_nop 1
	v_permlane32_swap_b32_e32 v43, v47
	v_permlane32_swap_b32_e32 v46, v132
	v_add_f32_e32 v43, v43, v47
	v_add_f32_e32 v46, v46, v132
	v_mov_b32_e32 v47, v43
	v_mov_b32_e32 v132, v46
	s_nop 1
	v_permlane16_swap_b32_e32 v43, v47
	v_permlane16_swap_b32_e32 v46, v132
	v_add_f32_e32 v43, v43, v47
	v_add_f32_e32 v46, v46, v132
	s_nop 1
	v_add_f32_dpp v43, v43, v43 row_ror:8 row_mask:0xf bank_mask:0xf
	v_add_f32_dpp v46, v46, v46 row_ror:8 row_mask:0xf bank_mask:0xf
	s_nop 0
	v_add_f32_dpp v43, v43, v43 row_ror:4 row_mask:0xf bank_mask:0xf
	v_add_f32_dpp v46, v46, v46 row_ror:4 row_mask:0xf bank_mask:0xf
	s_nop 0
	v_add_f32_dpp v43, v43, v43 quad_perm:[2,3,0,1] row_mask:0xf bank_mask:0xf
	v_add_f32_dpp v46, v46, v46 quad_perm:[2,3,0,1] row_mask:0xf bank_mask:0xf
	s_nop 0
	v_add_f32_dpp v61, v43, v43 quad_perm:[1,0,3,2] row_mask:0xf bank_mask:0xf
	v_add_f32_dpp v43, v46, v46 quad_perm:[1,0,3,2] row_mask:0xf bank_mask:0xf
	v_fmamk_f32 v27, v61, 0xba800000, v27
	v_fmac_f32_e32 v26, 0xba800000, v61
	v_fmamk_f32 v63, v61, 0xba800000, v33
	v_fmamk_f32 v62, v61, 0xba800000, v32
	v_fmamk_f32 v11, v43, 0xba800000, v11
	v_fmac_f32_e32 v10, 0xba800000, v43
	v_fmamk_f32 v31, v61, 0xba800000, v31
	v_fmac_f32_e32 v30, 0xba800000, v61
	v_fmamk_f32 v59, v61, 0xba800000, v29
	v_fmamk_f32 v58, v61, 0xba800000, v28
	v_fmamk_f32 v15, v43, 0xba800000, v15
	v_fmac_f32_e32 v14, 0xba800000, v43
	v_fmamk_f32 v51, v43, 0xba800000, v13
	v_fmamk_f32 v50, v43, 0xba800000, v12
	v_fmamk_f32 v33, v43, 0xba800000, v5
	v_fmamk_f32 v32, v43, 0xba800000, v4
	v_pk_mul_f32 v[4:5], v[26:27], v[26:27]
	v_pk_mul_f32 v[12:13], v[10:11], v[10:11]
	v_fmamk_f32 v23, v61, 0xba800000, v23
	v_fmac_f32_e32 v22, 0xba800000, v61
	v_fmamk_f32 v53, v43, 0xba800000, v17
	v_fmamk_f32 v52, v43, 0xba800000, v16
	v_fmamk_f32 v47, v43, 0xba800000, v9
	v_fmamk_f32 v46, v43, 0xba800000, v8
	v_fmamk_f32 v7, v43, 0xba800000, v7
	v_fmac_f32_e32 v6, 0xba800000, v43
	v_pk_mul_f32 v[8:9], v[58:59], v[58:59]
	v_pk_fma_f32 v[4:5], v[30:31], v[30:31], v[4:5]
	v_pk_mul_f32 v[16:17], v[50:51], v[50:51]
	v_pk_fma_f32 v[12:13], v[14:15], v[14:15], v[12:13]
	v_fmamk_f32 v57, v61, 0xba800000, v25
	v_fmamk_f32 v56, v61, 0xba800000, v24
	v_fmamk_f32 v19, v61, 0xba800000, v19
	v_fmac_f32_e32 v18, 0xba800000, v61
	v_fmamk_f32 v3, v43, 0xba800000, v3
	v_fmac_f32_e32 v2, 0xba800000, v43
	v_pk_fma_f32 v[8:9], v[62:63], v[62:63], v[8:9]
	v_pk_fma_f32 v[4:5], v[22:23], v[22:23], v[4:5]
	v_pk_fma_f32 v[16:17], v[52:53], v[52:53], v[16:17]
	v_pk_fma_f32 v[12:13], v[6:7], v[6:7], v[12:13]
	v_fmamk_f32 v55, v61, 0xba800000, v21
	v_fmamk_f32 v54, v61, 0xba800000, v20
	v_pk_fma_f32 v[8:9], v[56:57], v[56:57], v[8:9]
	v_pk_fma_f32 v[4:5], v[18:19], v[18:19], v[4:5]
	v_pk_fma_f32 v[16:17], v[46:47], v[46:47], v[16:17]
	v_pk_fma_f32 v[12:13], v[2:3], v[2:3], v[12:13]
	v_pk_fma_f32 v[8:9], v[54:55], v[54:55], v[8:9]
	v_pk_fma_f32 v[16:17], v[32:33], v[32:33], v[16:17]
	v_mov_b32_e32 v20, v12
	v_mov_b32_e32 v21, v4
	v_mov_b32_e32 v4, v13
	v_pk_add_f32 v[4:5], v[20:21], v[4:5]
	v_mov_b32_e32 v12, v16
	v_mov_b32_e32 v13, v8
	v_pk_add_f32 v[4:5], v[12:13], v[4:5]
	v_mov_b32_e32 v8, v17
	v_pk_add_f32 v[4:5], v[8:9], v[4:5]
	v_mov_b32_e32 v8, v4
	v_mov_b32_e32 v9, v5
	s_nop 1
	v_permlane32_swap_b32_e32 v4, v8
	v_permlane32_swap_b32_e32 v5, v9
	v_pk_add_f32 v[4:5], v[4:5], v[8:9]
	v_mov_b32_e32 v8, v4
	v_mov_b32_e32 v9, v5
	s_nop 1
	v_permlane16_swap_b32_e32 v4, v8
	v_permlane16_swap_b32_e32 v5, v9
	v_pk_add_f32 v[4:5], v[4:5], v[8:9]
	s_nop 1
	v_add_f32_dpp v4, v4, v4 row_ror:8 row_mask:0xf bank_mask:0xf
	v_add_f32_dpp v5, v5, v5 row_ror:8 row_mask:0xf bank_mask:0xf
	s_nop 0
	v_add_f32_dpp v4, v4, v4 row_ror:4 row_mask:0xf bank_mask:0xf
	v_add_f32_dpp v5, v5, v5 row_ror:4 row_mask:0xf bank_mask:0xf
	s_nop 0
	v_add_f32_dpp v4, v4, v4 quad_perm:[2,3,0,1] row_mask:0xf bank_mask:0xf
	v_add_f32_dpp v5, v5, v5 quad_perm:[2,3,0,1] row_mask:0xf bank_mask:0xf
	s_nop 0
	v_add_f32_dpp v4, v4, v4 quad_perm:[1,0,3,2] row_mask:0xf bank_mask:0xf
	v_add_f32_dpp v5, v5, v5 quad_perm:[1,0,3,2] row_mask:0xf bank_mask:0xf
	v_mov_b32_e32 v8, 0x3727c5ac
	v_pk_fma_f32 v[8:9], v[4:5], s[0:1], v[8:9] op_sel_hi:[1,0,0]
	s_mov_b32 s0, 0x800000
	v_mul_f32_e32 v4, 0x4b800000, v9
	v_cmp_gt_f32_e32 vcc, s0, v8
	v_cmp_gt_f32_e64 s[0:1], s0, v9
	s_nop 1
	v_cndmask_b32_e64 v4, v9, v4, s[0:1]
	v_rsq_f32_e32 v4, v4
	s_nop 0
	v_mul_f32_e32 v5, 0x45800000, v4
	v_cndmask_b32_e64 v4, v4, v5, s[0:1]
	v_mul_f32_e32 v5, 0x4b800000, v8
	v_cndmask_b32_e32 v5, v8, v5, vcc
	v_rsq_f32_e32 v5, v5
	s_nop 0
	v_mul_f32_e32 v8, 0x45800000, v5
	v_cndmask_b32_e32 v60, v5, v8, vcc
	s_and_saveexec_b64 s[0:1], s[46:47]
	s_cbranch_execz .LBB0_88
	v_readlane_b32 s4, v254, 30
	v_readlane_b32 s5, v254, 31
	v_mul_f32_e32 v12, 0x3a800000, v61
	v_mov_b32_e32 v13, v4
	v_lshl_add_u64 v[8:9], v[48:49], 3, s[4:5]
	global_store_dwordx2 v[8:9], v[12:13], off
	s_and_b64 exec, exec, s[38:39]
	s_cbranch_execz .LBB0_88
	v_mul_f32_e32 v12, 0x3a800000, v43
	v_lshl_add_u64 v[8:9], s[42:43], 3, v[8:9]
	v_mov_b32_e32 v13, v60
	global_store_dwordx2 v[8:9], v[12:13], off

.LBB0_146:
	v_add_u32_e32 v42, s42, v44
	s_mov_b32 s0, 0x8000
	v_cmp_gt_i32_e64 s[38:39], s0, v42
	v_ashrrev_i32_e32 v45, 31, v44
	v_lshlrev_b64 v[2:3], 12, v[44:45]
	v_cndmask_b32_e64 v4, v44, v42, s[38:39]
	v_ashrrev_i32_e32 v5, 31, v4
	v_lshlrev_b64 v[4:5], 12, v[4:5]
	v_lshl_add_u64 v[2:3], v[34:35], 0, v[2:3]
	v_lshl_add_u64 v[4:5], v[34:35], 0, v[4:5]
	global_load_dwordx4 v[30:33], v[2:3], off
	global_load_dwordx4 v[26:29], v[2:3], off offset:1024
	global_load_dwordx4 v[22:25], v[2:3], off offset:2048
	global_load_dwordx4 v[18:21], v[2:3], off offset:3072
	global_load_dwordx4 v[14:17], v[4:5], off
	global_load_dwordx4 v[10:13], v[4:5], off offset:1024
	global_load_dwordx4 v[6:9], v[4:5], off offset:2048
	s_nop 0
	global_load_dwordx4 v[2:5], v[4:5], off offset:3072
	s_mov_b32 s0, 0x3c800000
	s_mov_b32 s1, 0x3a800000
	s_mov_b32 s0, s1
	s_mov_b32 s2, 0x800000
	s_waitcnt vmcnt(6)
	v_pk_add_f32 v[48:49], v[30:31], v[26:27]
	v_pk_add_f32 v[46:47], v[32:33], v[28:29]
	s_waitcnt vmcnt(5)
	v_pk_add_f32 v[48:49], v[48:49], v[22:23]
	v_pk_add_f32 v[46:47], v[46:47], v[24:25]
	s_waitcnt vmcnt(4)
	v_pk_add_f32 v[48:49], v[48:49], v[18:19]
	v_pk_add_f32 v[46:47], v[46:47], v[20:21]
	v_add_f32_e32 v0, v48, v49
	v_add_f32_e32 v0, v46, v0
	s_waitcnt vmcnt(2)
	v_pk_add_f32 v[58:59], v[14:15], v[10:11]
	v_add_f32_e32 v0, v47, v0
	v_pk_add_f32 v[56:57], v[16:17], v[12:13]
	s_waitcnt vmcnt(1)
	v_pk_add_f32 v[58:59], v[58:59], v[6:7]
	v_pk_add_f32 v[56:57], v[56:57], v[8:9]
	s_waitcnt vmcnt(0)
	v_pk_add_f32 v[58:59], v[58:59], v[2:3]
	v_pk_add_f32 v[56:57], v[56:57], v[4:5]
	v_add_f32_e32 v43, v58, v59
	v_add_f32_e32 v43, v56, v43
	v_add_f32_e32 v43, v57, v43
	v_mov_b32_e32 v46, v0
	v_mov_b32_e32 v132, v43
	s_nop 1
	v_permlane32_swap_b32_e32 v0, v46
	v_permlane32_swap_b32_e32 v43, v132
	v_add_f32_e32 v0, v0, v46
	v_add_f32_e32 v43, v43, v132
	v_mov_b32_e32 v46, v0
	v_mov_b32_e32 v132, v43
	s_nop 1
	v_permlane16_swap_b32_e32 v0, v46
	v_permlane16_swap_b32_e32 v43, v132
	v_add_f32_e32 v0, v0, v46
	v_add_f32_e32 v43, v43, v132
	s_nop 1
	v_add_f32_dpp v0, v0, v0 row_ror:8 row_mask:0xf bank_mask:0xf
	v_add_f32_dpp v43, v43, v43 row_ror:8 row_mask:0xf bank_mask:0xf
	s_nop 0
	v_add_f32_dpp v0, v0, v0 row_ror:4 row_mask:0xf bank_mask:0xf
	v_add_f32_dpp v43, v43, v43 row_ror:4 row_mask:0xf bank_mask:0xf
	s_nop 0
	v_add_f32_dpp v0, v0, v0 quad_perm:[2,3,0,1] row_mask:0xf bank_mask:0xf
	v_add_f32_dpp v43, v43, v43 quad_perm:[2,3,0,1] row_mask:0xf bank_mask:0xf
	s_nop 0
	v_add_f32_dpp v46, v0, v0 quad_perm:[1,0,3,2] row_mask:0xf bank_mask:0xf
	v_add_f32_dpp v43, v43, v43 quad_perm:[1,0,3,2] row_mask:0xf bank_mask:0xf
	v_fmamk_f32 v27, v46, 0xba800000, v27
	v_fmac_f32_e32 v26, 0xba800000, v46
	v_fmamk_f32 v31, v46, 0xba800000, v31
	v_fmac_f32_e32 v30, 0xba800000, v46
	v_fmamk_f32 v11, v43, 0xba800000, v11
	v_fmac_f32_e32 v10, 0xba800000, v43
	v_fmamk_f32 v29, v46, 0xba800000, v29
	v_fmamk_f32 v28, v46, 0xba800000, v28
	v_fmamk_f32 v15, v43, 0xba800000, v15
	v_fmac_f32_e32 v14, 0xba800000, v43
	v_fmamk_f32 v13, v43, 0xba800000, v13
	v_fmamk_f32 v12, v43, 0xba800000, v12
	v_pk_mul_f32 v[48:49], v[26:27], v[26:27]
	v_pk_mul_f32 v[58:59], v[10:11], v[10:11]
	v_fmamk_f32 v33, v46, 0xba800000, v33
	v_fmamk_f32 v32, v46, 0xba800000, v32
	v_fmamk_f32 v23, v46, 0xba800000, v23
	v_fmac_f32_e32 v22, 0xba800000, v46
	v_fmamk_f32 v17, v43, 0xba800000, v17
	v_fmamk_f32 v16, v43, 0xba800000, v16
	v_fmamk_f32 v7, v43, 0xba800000, v7
	v_fmac_f32_e32 v6, 0xba800000, v43
	v_pk_mul_f32 v[56:57], v[28:29], v[28:29]
	v_pk_fma_f32 v[48:49], v[30:31], v[30:31], v[48:49]
	v_pk_mul_f32 v[60:61], v[12:13], v[12:13]
	v_pk_fma_f32 v[58:59], v[14:15], v[14:15], v[58:59]
	v_fmamk_f32 v25, v46, 0xba800000, v25
	v_fmamk_f32 v24, v46, 0xba800000, v24
	v_fmamk_f32 v19, v46, 0xba800000, v19
	v_fmac_f32_e32 v18, 0xba800000, v46
	v_fmamk_f32 v9, v43, 0xba800000, v9
	v_fmamk_f32 v8, v43, 0xba800000, v8
	v_fmamk_f32 v3, v43, 0xba800000, v3
	v_fmac_f32_e32 v2, 0xba800000, v43
	v_pk_fma_f32 v[56:57], v[32:33], v[32:33], v[56:57]
	v_pk_fma_f32 v[48:49], v[22:23], v[22:23], v[48:49]
	v_pk_fma_f32 v[60:61], v[16:17], v[16:17], v[60:61]
	v_pk_fma_f32 v[58:59], v[6:7], v[6:7], v[58:59]
	v_fmamk_f32 v21, v46, 0xba800000, v21
	v_fmamk_f32 v20, v46, 0xba800000, v20
	v_fmamk_f32 v5, v43, 0xba800000, v5
	v_fmamk_f32 v4, v43, 0xba800000, v4
	v_pk_fma_f32 v[56:57], v[24:25], v[24:25], v[56:57]
	v_pk_fma_f32 v[48:49], v[18:19], v[18:19], v[48:49]
	v_pk_fma_f32 v[60:61], v[8:9], v[8:9], v[60:61]
	v_pk_fma_f32 v[58:59], v[2:3], v[2:3], v[58:59]
	v_pk_fma_f32 v[56:57], v[20:21], v[20:21], v[56:57]
	v_pk_fma_f32 v[60:61], v[4:5], v[4:5], v[60:61]
	v_mov_b32_e32 v62, v58
	v_mov_b32_e32 v63, v48
	v_mov_b32_e32 v48, v59
	v_pk_add_f32 v[48:49], v[62:63], v[48:49]
	v_mov_b32_e32 v58, v60
	v_mov_b32_e32 v59, v56
	v_pk_add_f32 v[48:49], v[58:59], v[48:49]
	v_mov_b32_e32 v56, v61
	v_pk_add_f32 v[48:49], v[56:57], v[48:49]
	v_mov_b32_e32 v56, v48
	v_mov_b32_e32 v57, v49
	s_nop 1
	v_permlane32_swap_b32_e32 v48, v56
	v_permlane32_swap_b32_e32 v49, v57
	v_pk_add_f32 v[48:49], v[48:49], v[56:57]
	v_mov_b32_e32 v56, v48
	v_mov_b32_e32 v57, v49
	s_nop 1
	v_permlane16_swap_b32_e32 v48, v56
	v_permlane16_swap_b32_e32 v49, v57
	v_pk_add_f32 v[48:49], v[48:49], v[56:57]
	s_nop 1
	v_add_f32_dpp v48, v48, v48 row_ror:8 row_mask:0xf bank_mask:0xf
	v_add_f32_dpp v49, v49, v49 row_ror:8 row_mask:0xf bank_mask:0xf
	s_nop 0
	v_add_f32_dpp v48, v48, v48 row_ror:4 row_mask:0xf bank_mask:0xf
	v_add_f32_dpp v49, v49, v49 row_ror:4 row_mask:0xf bank_mask:0xf
	s_nop 0
	v_add_f32_dpp v48, v48, v48 quad_perm:[2,3,0,1] row_mask:0xf bank_mask:0xf
	v_add_f32_dpp v49, v49, v49 quad_perm:[2,3,0,1] row_mask:0xf bank_mask:0xf
	s_nop 0
	v_add_f32_dpp v48, v48, v48 quad_perm:[1,0,3,2] row_mask:0xf bank_mask:0xf
	v_add_f32_dpp v49, v49, v49 quad_perm:[1,0,3,2] row_mask:0xf bank_mask:0xf
	v_mov_b32_e32 v0, 0x3727c5ac
	s_nop 0
	v_pk_fma_f32 v[48:49], v[48:49], s[0:1], v[0:1] op_sel_hi:[1,0,0]
	s_nop 0
	v_mul_f32_e32 v0, 0x4b800000, v49
	v_cmp_gt_f32_e64 s[40:41], s2, v49
	v_cmp_gt_f32_e64 s[0:1], s2, v48
	s_nop 0
	v_cndmask_b32_e64 v0, v49, v0, s[40:41]
	v_rsq_f32_e32 v0, v0
	s_nop 0
	v_mul_f32_e32 v47, 0x45800000, v0
	v_cndmask_b32_e64 v0, v0, v47, s[40:41]
	v_mul_f32_e32 v47, 0x4b800000, v48
	v_cndmask_b32_e64 v47, v48, v47, s[0:1]
	v_rsq_f32_e32 v47, v47
	s_nop 0
	v_mul_f32_e32 v48, 0x45800000, v47
	v_cndmask_b32_e64 v47, v47, v48, s[0:1]
	s_and_saveexec_b64 s[0:1], vcc
	s_cbranch_execz .LBB0_149
	v_readlane_b32 s4, v254, 30
	v_readlane_b32 s5, v254, 31
	v_mul_f32_e32 v56, 0x3a800000, v46
	v_mov_b32_e32 v57, v0
	v_lshl_add_u64 v[48:49], v[44:45], 3, s[4:5]
	global_store_dwordx2 v[48:49], v[56:57], off
	s_and_b64 exec, exec, s[38:39]
	s_cbranch_execz .LBB0_149
	v_mul_f32_e32 v46, 0x3a800000, v43
	v_lshl_add_u64 v[48:49], s[42:43], 3, v[48:49]
	global_store_dwordx2 v[48:49], v[46:47], off
